# cross-attention sample unit: Q fragments fetched a stage early with counted vmcnt so the K/V stream stays in flight across barriers; PV loop LDS reads batched with counted lgkmcnt; phase-3 item interl
# speedup vs baseline: 1.0417x; 1.0022x over previous
.LBB0_154:
	s_or_b64 exec, exec, s[6:7]
	v_mov_b32_e32 v0, s86
	s_waitcnt lgkmcnt(0)
	s_barrier
	ds_read_b32 v0, v0
	s_mov_b64 s[6:7], -1
	s_waitcnt lgkmcnt(0)
	v_cmp_lt_i32_e32 vcc, s58, v0
	v_readfirstlane_b32 s24, v0
	s_cbranch_vccnz .LBB0_151
	s_bitcmp0_b32 s24, 0
	s_cbranch_scc1 .LBB0_179
	s_andn2_b64 vcc, exec, s[12:13]
	s_cbranch_vccnz .LBB0_178
	s_ashr_i32 s0, s24, 3
	s_add_i32 s20, s0, s52
	s_mov_b32 s71, s69
	s_mov_b64 s[68:69], s[76:77]
	s_mov_b64 s[66:67], s[78:79]
	s_mov_b64 s[64:65], s[80:81]
	s_ashr_i32 s21, s20, 31
	v_readlane_b32 s72, v253, 42
	s_and_b32 s25, s24, -8
	s_lshl_b64 s[22:23], s[20:21], 20
	v_readlane_b32 s82, v253, 52
	v_readlane_b32 s83, v253, 53
	s_add_u32 s21, s82, s22
	s_addc_u32 s55, s83, s23
	s_lshl_b32 s0, s24, 7
	s_and_b32 s0, s0, 0x300
	s_mov_b64 s[6:7], s[94:95]
	v_mov_b32_e32 v216, v191
	s_lshl_b32 s20, s0, 2
	s_add_u32 s54, s21, s20
	v_lshlrev_b32_e32 v0, 5, v216
	v_ashrrev_i32_e32 v74, 3, v216
	v_add_u32_e32 v217, 0x200, v216
	s_addc_u32 s55, s55, 0
	v_and_b32_e32 v152, 0xe0, v0
	v_ashrrev_i32_e32 v75, 31, v74
	v_ashrrev_i32_e32 v76, 3, v217
	v_lshl_add_u64 v[0:1], s[54:55], 0, v[152:153]
	v_lshlrev_b64 v[2:3], 12, v[74:75]
	v_ashrrev_i32_e32 v77, 31, v76
	v_lshl_add_u64 v[32:33], v[0:1], 0, v[2:3]
	v_lshlrev_b64 v[2:3], 12, v[76:77]
	v_lshl_add_u64 v[34:35], v[0:1], 0, v[2:3]
	v_add_u32_e32 v2, 0x400, v216
	v_ashrrev_i32_e32 v78, 3, v2
	v_ashrrev_i32_e32 v79, 31, v78
	v_lshlrev_b64 v[2:3], 12, v[78:79]
	v_lshl_add_u64 v[36:37], v[0:1], 0, v[2:3]
	v_add_u32_e32 v2, 0x600, v216
	v_ashrrev_i32_e32 v80, 3, v2
	v_ashrrev_i32_e32 v81, 31, v80
	global_load_dwordx4 v[42:45], v[32:33], off offset:16
	global_load_dwordx4 v[46:49], v[32:33], off
	global_load_dwordx4 v[50:53], v[34:35], off offset:16
	global_load_dwordx4 v[54:57], v[34:35], off
	v_lshlrev_b64 v[2:3], 12, v[80:81]
	global_load_dwordx4 v[58:61], v[36:37], off offset:16
	global_load_dwordx4 v[62:65], v[36:37], off
	v_lshl_add_u64 v[38:39], v[0:1], 0, v[2:3]
	global_load_dwordx4 v[66:69], v[38:39], off offset:16
	global_load_dwordx4 v[70:73], v[38:39], off
	v_lshlrev_b32_e32 v41, 4, v216
	v_add_u32_e32 v40, s25, v97
	v_and_b32_e32 v41, 0x70, v41
	v_readlane_b32 s84, v253, 54
	v_add_u32_e32 v82, 0, v41
	v_ashrrev_i32_e32 v41, 31, v40
	v_readlane_b32 s85, v253, 55
	s_add_u32 s21, s84, s22
	v_lshlrev_b64 v[162:163], 11, v[40:41]
	s_addc_u32 s22, s85, s23
	s_movk_i32 s23, 0x90
	v_lshl_add_u64 v[40:41], s[6:7], 0, v[162:163]
	s_lshl_b32 s0, s0, 1
	v_mad_u64_u32 v[164:165], s[54:55], v74, s23, v[82:83]
	v_mad_u64_u32 v[166:167], s[54:55], v76, s23, v[82:83]
	v_mad_u64_u32 v[168:169], s[54:55], v78, s23, v[82:83]
	v_mad_u64_u32 v[170:171], s[54:55], v80, s23, v[82:83]
	v_lshl_add_u64 v[40:41], v[40:41], 0, s[0:1]
	v_lshlrev_b32_e32 v152, 1, v96
	global_load_dwordx4 v[0:3], v[32:33], off offset:272
	global_load_dwordx4 v[20:23], v[32:33], off offset:256
	global_load_dwordx4 v[4:7], v[34:35], off offset:272
	global_load_dwordx4 v[24:27], v[34:35], off offset:256
	global_load_dwordx4 v[8:11], v[36:37], off offset:272
	global_load_dwordx4 v[28:31], v[36:37], off offset:256
	global_load_dwordx4 v[12:15], v[38:39], off offset:272
	global_load_dwordx4 v[16:19], v[38:39], off offset:256
	v_lshl_add_u64 v[40:41], v[40:41], 0, v[152:153]
	s_mov_b64 s[54:55], 0x1b500000
	s_mov_b32 s23, 0x1b500000
	v_lshl_add_u64 v[172:173], v[40:41], 0, s[54:55]
	v_add_co_u32_e32 v40, vcc, s23, v40
	s_add_u32 s20, s21, s20
	s_nop 0
	v_addc_co_u32_e32 v41, vcc, 0, v41, vcc
	global_load_dwordx4 v[226:229], v[172:173], off
	global_load_dwordx4 v[230:233], v[172:173], off offset:64
	s_addc_u32 s21, s22, 0
	s_mov_b64 s[22:23], 0x1000
	v_readlane_b32 s73, v253, 43
	v_readlane_b32 s74, v253, 44
	v_readlane_b32 s75, v253, 45
	v_readlane_b32 s76, v253, 46
	v_readlane_b32 s77, v253, 47
	v_readlane_b32 s78, v253, 48
	v_readlane_b32 s79, v253, 49
	v_readlane_b32 s80, v253, 50
	v_readlane_b32 s81, v253, 51
	v_readlane_b32 s86, v253, 56
	v_readlane_b32 s87, v253, 57
	s_waitcnt vmcnt(10)
	v_cvt_pk_bf16_f32 v46, v46, v47
	v_cvt_pk_bf16_f32 v47, v48, v49
	v_cvt_pk_bf16_f32 v48, v42, v43
	v_cvt_pk_bf16_f32 v49, v44, v45
	v_cvt_pk_bf16_f32 v42, v54, v55
	v_cvt_pk_bf16_f32 v43, v56, v57
	v_cvt_pk_bf16_f32 v44, v50, v51
	v_cvt_pk_bf16_f32 v45, v52, v53
	ds_write_b128 v164, v[46:49]
	ds_write_b128 v166, v[42:45]
	v_cvt_pk_bf16_f32 v42, v62, v63
	v_cvt_pk_bf16_f32 v43, v64, v65
	v_cvt_pk_bf16_f32 v44, v58, v59
	v_cvt_pk_bf16_f32 v45, v60, v61
	ds_write_b128 v168, v[42:45]
	v_cvt_pk_bf16_f32 v42, v70, v71
	v_cvt_pk_bf16_f32 v43, v72, v73
	v_cvt_pk_bf16_f32 v44, v66, v67
	v_cvt_pk_bf16_f32 v45, v68, v69
	ds_write_b128 v170, v[42:45]
	global_load_dwordx4 v[234:237], v[172:173], off offset:128
	global_load_dwordx4 v[238:241], v[172:173], off offset:192
	global_load_dwordx4 v[88:91], v[32:33], off offset:528
	global_load_dwordx4 v[92:95], v[32:33], off offset:512
	global_load_dwordx4 v[72:75], v[34:35], off offset:528
	global_load_dwordx4 v[80:83], v[34:35], off offset:512
	global_load_dwordx4 v[64:67], v[36:37], off offset:528
	global_load_dwordx4 v[68:71], v[36:37], off offset:512
	global_load_dwordx4 v[76:79], v[38:39], off offset:528
	global_load_dwordx4 v[84:87], v[38:39], off offset:512
	s_waitcnt lgkmcnt(0)
	s_barrier
	s_waitcnt vmcnt(10)
	ds_read_b128 v[44:47], v193
	ds_read_b128 v[52:55], v193 offset:64
	ds_read_b128 v[48:51], v193 offset:2304
	v_cvt_pk_bf16_f32 v20, v20, v21
	v_cvt_pk_bf16_f32 v21, v22, v23
	v_cvt_pk_bf16_f32 v22, v0, v1
	v_cvt_pk_bf16_f32 v23, v2, v3
	v_cvt_pk_bf16_f32 v0, v24, v25
	v_cvt_pk_bf16_f32 v1, v26, v27
	v_cvt_pk_bf16_f32 v2, v4, v5
	v_cvt_pk_bf16_f32 v3, v6, v7
	s_waitcnt lgkmcnt(0)
	v_mfma_f32_16x16x32_bf16 v[44:47], v[44:47], v[226:229], 0
	v_mfma_f32_16x16x32_bf16 v[40:43], v[48:51], v[226:229], 0
	v_mfma_f32_16x16x32_bf16 v[218:221], v[52:55], v[230:233], v[44:47]
	s_nop 3
	ds_read_b128 v[44:47], v193 offset:2368
	s_waitcnt lgkmcnt(0)
	s_barrier
	ds_write_b128 v164, v[20:23]
	ds_write_b128 v166, v[0:3]
	v_cvt_pk_bf16_f32 v0, v28, v29
	v_cvt_pk_bf16_f32 v1, v30, v31
	v_cvt_pk_bf16_f32 v2, v8, v9
	v_cvt_pk_bf16_f32 v3, v10, v11
	ds_write_b128 v168, v[0:3]
	v_cvt_pk_bf16_f32 v0, v16, v17
	v_cvt_pk_bf16_f32 v1, v18, v19
	v_cvt_pk_bf16_f32 v2, v12, v13
	v_cvt_pk_bf16_f32 v3, v14, v15
	ds_write_b128 v170, v[0:3]
	v_mfma_f32_16x16x32_bf16 v[222:225], v[44:47], v[230:233], v[40:43]
	global_load_dwordx4 v[226:229], v[172:173], off offset:256
	global_load_dwordx4 v[230:233], v[172:173], off offset:320
	global_load_dwordx4 v[56:59], v[32:33], off offset:784
	global_load_dwordx4 v[60:63], v[32:33], off offset:768
	global_load_dwordx4 v[48:51], v[34:35], off offset:784
	global_load_dwordx4 v[52:55], v[34:35], off offset:768
	global_load_dwordx4 v[40:43], v[36:37], off offset:784
	global_load_dwordx4 v[44:47], v[36:37], off offset:768
	s_nop 0
	global_load_dwordx4 v[32:35], v[38:39], off offset:784
	s_nop 0
	global_load_dwordx4 v[36:39], v[38:39], off offset:768
	s_waitcnt lgkmcnt(0)
	s_barrier
	s_waitcnt vmcnt(0)
	ds_read_b128 v[4:7], v193
	ds_read_b128 v[12:15], v193 offset:64
	ds_read_b128 v[8:11], v193 offset:2304
	s_waitcnt lgkmcnt(0)
	v_mfma_f32_16x16x32_bf16 v[4:7], v[4:7], v[234:237], v[218:221]
	v_cvt_pk_bf16_f32 v60, v60, v61
	v_cvt_pk_bf16_f32 v61, v62, v63
	v_cvt_pk_bf16_f32 v62, v56, v57
	v_mfma_f32_16x16x32_bf16 v[0:3], v[8:11], v[234:237], v[222:225]
	v_cvt_pk_bf16_f32 v63, v58, v59
	v_cvt_pk_bf16_f32 v52, v52, v53
	v_cvt_pk_bf16_f32 v53, v54, v55
	v_cvt_pk_bf16_f32 v54, v48, v49
	v_cvt_pk_bf16_f32 v55, v50, v51
	v_cvt_pk_bf16_f32 v44, v44, v45
	v_cvt_pk_bf16_f32 v45, v46, v47
	v_cvt_pk_bf16_f32 v46, v40, v41
	v_cvt_pk_bf16_f32 v47, v42, v43
	v_cvt_pk_bf16_f32 v36, v36, v37
	v_cvt_pk_bf16_f32 v37, v38, v39
	v_cvt_pk_bf16_f32 v38, v32, v33
	s_waitcnt lgkmcnt(0)
	v_mfma_f32_16x16x32_bf16 v[218:221], v[12:15], v[238:241], v[4:7]
	s_nop 2
	ds_read_b128 v[4:7], v193 offset:2368
	s_waitcnt lgkmcnt(0)
	s_barrier
	v_mfma_f32_16x16x32_bf16 v[222:225], v[4:7], v[238:241], v[0:3]
	s_nop 2
	v_cvt_pk_bf16_f32 v0, v92, v93
	v_cvt_pk_bf16_f32 v1, v94, v95
	v_cvt_pk_bf16_f32 v2, v88, v89
	v_cvt_pk_bf16_f32 v3, v90, v91
	ds_write_b128 v164, v[0:3]
	v_cvt_pk_bf16_f32 v0, v80, v81
	v_cvt_pk_bf16_f32 v1, v82, v83
	v_cvt_pk_bf16_f32 v2, v72, v73
	v_cvt_pk_bf16_f32 v3, v74, v75
	ds_write_b128 v166, v[0:3]
	v_cvt_pk_bf16_f32 v0, v68, v69
	v_cvt_pk_bf16_f32 v1, v70, v71
	v_cvt_pk_bf16_f32 v2, v64, v65
	v_cvt_pk_bf16_f32 v3, v66, v67
	ds_write_b128 v168, v[0:3]
	v_cvt_pk_bf16_f32 v0, v84, v85
	v_cvt_pk_bf16_f32 v1, v86, v87
	v_cvt_pk_bf16_f32 v2, v76, v77
	v_cvt_pk_bf16_f32 v3, v78, v79
	ds_write_b128 v170, v[0:3]
	v_lshlrev_b32_e32 v0, 13, v216
	v_ashrrev_i32_e32 v2, 4, v216
	v_and_b32_e32 v152, 0xfe000, v0
	v_and_b32_e32 v82, -8, v2
	v_lshl_add_u64 v[0:1], s[20:21], 0, v[152:153]
	v_ashrrev_i32_e32 v83, 31, v82
	v_lshl_add_u64 v[72:73], v[82:83], 2, v[0:1]
	s_movk_i32 s20, 0x1000
	v_add_co_u32_e32 v76, vcc, s20, v72
	v_lshl_add_u64 v[2:3], v[72:73], 0, s[22:23]
	s_nop 0
	v_addc_co_u32_e32 v77, vcc, 0, v73, vcc
	global_load_dwordx4 v[234:237], v[172:173], off offset:384
	global_load_dwordx4 v[238:241], v[172:173], off offset:448
	global_load_dwordx4 v[16:19], v[72:73], off offset:16
	global_load_dwordx4 v[20:23], v[72:73], off
	global_load_dwordx4 v[28:31], v[76:77], off
	global_load_dwordx4 v[24:27], v[2:3], off offset:16
	v_ashrrev_i32_e32 v2, 4, v217
	v_and_b32_e32 v80, -8, v2
	v_ashrrev_i32_e32 v81, 31, v80
	v_lshl_add_u64 v[74:75], v[80:81], 2, v[0:1]
	v_add_co_u32_e32 v78, vcc, s20, v74
	v_lshl_add_u64 v[8:9], v[74:75], 0, s[22:23]
	s_nop 0
	v_addc_co_u32_e32 v79, vcc, 0, v75, vcc
	global_load_dwordx4 v[0:3], v[74:75], off offset:16
	global_load_dwordx4 v[4:7], v[74:75], off
	global_load_dwordx4 v[12:15], v[78:79], off
	s_nop 0
	global_load_dwordx4 v[8:11], v[8:9], off offset:16
	s_waitcnt lgkmcnt(0)
	s_barrier
	s_waitcnt vmcnt(10)
	ds_read_b128 v[68:71], v193
	ds_read_b128 v[88:91], v193 offset:64
	ds_read_b128 v[84:87], v193 offset:2304
	s_waitcnt lgkmcnt(0)
	v_mfma_f32_16x16x32_bf16 v[68:71], v[68:71], v[226:229], v[218:221]
	v_cvt_pk_bf16_f32 v39, v34, v35
	s_mov_b64 s[20:21], 0x1100
	v_lshl_add_u64 v[32:33], v[72:73], 0, s[20:21]
	v_mfma_f32_16x16x32_bf16 v[64:67], v[84:87], v[226:229], v[222:225]
	v_mfma_f32_16x16x32_bf16 v[68:71], v[88:91], v[230:233], v[68:71]
	ds_read_b128 v[88:91], v193 offset:2368
	s_waitcnt lgkmcnt(0)
	s_barrier
	ds_write_b128 v164, v[60:63]
	ds_write_b128 v166, v[52:55]
	ds_write_b128 v168, v[44:47]
	ds_write_b128 v170, v[36:39]
	v_lshl_add_u64 v[44:45], v[74:75], 0, s[20:21]
	v_mfma_f32_16x16x32_bf16 v[64:67], v[88:91], v[230:233], v[64:67]
	global_load_dwordx4 v[48:51], v[72:73], off offset:272
	global_load_dwordx4 v[60:63], v[72:73], off offset:256
	global_load_dwordx4 v[56:59], v[76:77], off offset:256
	global_load_dwordx4 v[52:55], v[32:33], off offset:16
	s_nop 0
	global_load_dwordx4 v[32:35], v[74:75], off offset:272
	global_load_dwordx4 v[36:39], v[74:75], off offset:256
	global_load_dwordx4 v[40:43], v[78:79], off offset:256
	s_nop 0
	global_load_dwordx4 v[44:47], v[44:45], off offset:16
	s_waitcnt lgkmcnt(0)
	s_barrier
	s_waitcnt vmcnt(8)
	ds_read_b128 v[88:91], v193
	s_waitcnt lgkmcnt(0)
	v_mfma_f32_16x16x32_bf16 v[68:71], v[88:91], v[234:237], v[68:71]
	ds_read_b128 v[88:91], v193 offset:2304
	s_waitcnt lgkmcnt(0)
	v_mfma_f32_16x16x32_bf16 v[64:67], v[88:91], v[234:237], v[64:67]
	ds_read_b128 v[88:91], v193 offset:64
	s_waitcnt lgkmcnt(0)
	v_mfma_f32_16x16x32_bf16 v[68:71], v[88:91], v[238:241], v[68:71]
	ds_read_b128 v[88:91], v193 offset:2368
	s_nop 6
	v_max_f32_e32 v81, v69, v69
	s_waitcnt lgkmcnt(0)
	v_mfma_f32_16x16x32_bf16 v[64:67], v[88:91], v[238:241], v[64:67]
	v_max_f32_e32 v83, v68, v68
	v_max_f32_e32 v81, v83, v81
	v_max_f32_e32 v83, v71, v71
	v_max_f32_e32 v84, v70, v70
	v_max_f32_e32 v83, v84, v83
	s_nop 2
	v_max_f32_e32 v84, v67, v67
	v_max_f32_e32 v85, v66, v66
	v_max_f32_e32 v84, v85, v84
	v_max3_f32 v84, v64, v65, v84
	v_max3_f32 v83, v81, v83, v84
	v_and_b32_e32 v84, 64, v188
	v_xor_b32_e32 v81, 16, v188
	v_add_u32_e32 v84, 64, v84
	v_cmp_lt_i32_e32 vcc, v81, v84
	s_nop 1
	v_cndmask_b32_e32 v81, v188, v81, vcc
	v_lshlrev_b32_e32 v81, 2, v81
	ds_bpermute_b32 v85, v81, v83
	s_waitcnt lgkmcnt(0)
	v_max_f32_e32 v85, v85, v85
	v_max_f32_e32 v85, v83, v85
	v_xor_b32_e32 v83, 32, v188
	v_cmp_lt_i32_e32 vcc, v83, v84
	s_nop 1
	v_cndmask_b32_e32 v83, v188, v83, vcc
	v_lshlrev_b32_e32 v83, 2, v83
	ds_bpermute_b32 v84, v83, v85
	s_waitcnt lgkmcnt(0)
	v_max_f32_e32 v84, v84, v84
	v_max_f32_e32 v84, v85, v84
	s_and_saveexec_b64 s[20:21], s[8:9]
	ds_write_b32 v212, v84 offset:45312
	s_or_b64 exec, exec, s[20:21]
	v_add_u32_e32 v88, 0xb000, v174
	s_waitcnt lgkmcnt(0)
	s_barrier
	ds_read2_b32 v[86:87], v88 offset0:64 offset1:80
	s_waitcnt lgkmcnt(0)
	v_max3_f32 v86, v84, v86, v87
	ds_read2_b32 v[84:85], v88 offset0:96 offset1:112
	s_waitcnt lgkmcnt(0)
	v_max3_f32 v86, v86, v84, v85
	ds_read2_b32 v[84:85], v88 offset0:128 offset1:144
	s_waitcnt lgkmcnt(0)
	v_max3_f32 v86, v86, v84, v85
	ds_read2_b32 v[84:85], v88 offset0:160 offset1:176
	s_waitcnt lgkmcnt(0)
	v_max3_f32 v84, v86, v84, v85
	v_sub_f32_e32 v68, v68, v84
	v_mul_f32_e32 v68, 0x3fb8aa3b, v68
	v_sub_f32_e32 v69, v69, v84
	v_exp_f32_e32 v68, v68
	v_mul_f32_e32 v69, 0x3fb8aa3b, v69
	v_sub_f32_e32 v70, v70, v84
	v_exp_f32_e32 v69, v69
	v_mul_f32_e32 v70, 0x3fb8aa3b, v70
	v_sub_f32_e32 v71, v71, v84
	v_exp_f32_e32 v70, v70
	v_mul_f32_e32 v71, 0x3fb8aa3b, v71
	v_sub_f32_e32 v64, v64, v84
	v_exp_f32_e32 v71, v71
	v_mul_f32_e32 v64, 0x3fb8aa3b, v64
	v_sub_f32_e32 v65, v65, v84
	v_add_f32_e32 v85, 0, v68
	v_exp_f32_e32 v64, v64
	v_mul_f32_e32 v65, 0x3fb8aa3b, v65
	v_sub_f32_e32 v66, v66, v84
	v_add_f32_e32 v85, v69, v85
	v_exp_f32_e32 v65, v65
	v_mul_f32_e32 v66, 0x3fb8aa3b, v66
	v_sub_f32_e32 v67, v67, v84
	v_add_f32_e32 v85, v70, v85
	v_exp_f32_e32 v66, v66
	v_mul_f32_e32 v67, 0x3fb8aa3b, v67
	v_add_f32_e32 v85, v71, v85
	v_exp_f32_e32 v67, v67
	v_cvt_pk_bf16_f32 v68, v68, v69
	v_cvt_pk_bf16_f32 v69, v70, v71
	v_add_f32_e32 v70, v64, v85
	v_add_f32_e32 v70, v65, v70
	v_add_f32_e32 v70, v66, v70
	v_add_f32_e32 v70, v67, v70
	v_cvt_pk_bf16_f32 v64, v64, v65
	v_cvt_pk_bf16_f32 v65, v66, v67
	ds_write2_b64 v213, v[68:69], v[64:65] offset1:4
	ds_bpermute_b32 v64, v81, v70
	s_waitcnt lgkmcnt(0)
	v_add_f32_e32 v64, v70, v64
	ds_bpermute_b32 v65, v83, v64
	s_and_saveexec_b64 s[20:21], s[8:9]
	s_cbranch_execz .LBB0_161
	s_waitcnt lgkmcnt(0)
	v_add_f32_e32 v64, v64, v65
	ds_write_b32 v212, v64 offset:45824

.LBB0_165:
	s_waitcnt vmcnt(8)
	v_cvt_pk_bf16_f32 v60, v60, v61
	v_cvt_pk_bf16_f32 v48, v48, v49
	v_cvt_pk_bf16_f32 v49, v50, v51
	v_cvt_pk_bf16_f32 v50, v56, v57
	v_cvt_pk_bf16_f32 v52, v52, v53
	v_cvt_pk_bf16_f32 v53, v54, v55
	v_and_b32_e32 v54, 0xffff, v60
	v_lshrrev_b32_e32 v55, 16, v60
	v_cvt_pk_bf16_f32 v61, v62, v63
	v_lshl_or_b32 v54, v50, 16, v54
	v_and_or_b32 v50, v50, s59, v55
	s_waitcnt lgkmcnt(0)
	s_barrier
	v_cvt_pk_bf16_f32 v51, v58, v59
	ds_write2_b32 v69, v54, v50 offset1:132
	v_and_b32_e32 v50, 0xffff, v61
	v_lshrrev_b32_e32 v54, 16, v61
	v_lshl_or_b32 v50, v51, 16, v50
	v_and_or_b32 v51, v51, s59, v54
	ds_write2_b32 v70, v50, v51 offset0:8 offset1:140
	v_and_b32_e32 v50, 0xffff, v48
	v_lshrrev_b32_e32 v48, 16, v48
	v_lshl_or_b32 v50, v52, 16, v50
	v_and_or_b32 v48, v52, s59, v48
	v_cvt_pk_bf16_f32 v36, v36, v37
	ds_write2_b32 v81, v50, v48 offset0:16 offset1:148
	v_and_b32_e32 v48, 0xffff, v49
	v_lshrrev_b32_e32 v49, 16, v49
	v_cvt_pk_bf16_f32 v32, v32, v33
	v_cvt_pk_bf16_f32 v33, v34, v35
	v_cvt_pk_bf16_f32 v34, v40, v41
	v_and_b32_e32 v40, 0xffff, v36
	v_lshrrev_b32_e32 v36, 16, v36
	v_lshl_or_b32 v48, v53, 16, v48
	v_and_or_b32 v49, v53, s59, v49
	v_cvt_pk_bf16_f32 v37, v38, v39
	v_lshl_or_b32 v40, v34, 16, v40
	v_and_or_b32 v34, v34, s59, v36
	ds_write2_b32 v82, v48, v49 offset0:24 offset1:156
	v_cvt_pk_bf16_f32 v35, v42, v43
	ds_write2_b32 v71, v40, v34 offset1:132
	v_and_b32_e32 v34, 0xffff, v37
	v_lshrrev_b32_e32 v36, 16, v37
	v_lshl_or_b32 v34, v35, 16, v34
	v_and_or_b32 v35, v35, s59, v36
	v_cvt_pk_bf16_f32 v38, v44, v45
	ds_write2_b32 v80, v34, v35 offset0:8 offset1:140
	v_and_b32_e32 v34, 0xffff, v32
	v_lshrrev_b32_e32 v32, 16, v32
	v_lshl_or_b32 v34, v38, 16, v34
	v_and_or_b32 v32, v38, s59, v32
	v_cvt_pk_bf16_f32 v39, v46, v47
	ds_write2_b32 v83, v34, v32 offset0:16 offset1:148
	v_and_b32_e32 v32, 0xffff, v33
	v_lshrrev_b32_e32 v33, 16, v33
	v_lshl_or_b32 v32, v39, 16, v32
	v_and_or_b32 v33, v39, s59, v33
	s_mov_b64 s[22:23], 0x1300
	ds_write2_b32 v84, v32, v33 offset0:24 offset1:156
	v_lshl_add_u64 v[32:33], v[72:73], 0, s[22:23]
	global_load_dwordx4 v[48:51], v[72:73], off offset:784
	global_load_dwordx4 v[60:63], v[72:73], off offset:768
	global_load_dwordx4 v[56:59], v[76:77], off offset:768
	global_load_dwordx4 v[52:55], v[32:33], off offset:16
	s_nop 0
	global_load_dwordx4 v[32:35], v[74:75], off offset:784
	global_load_dwordx4 v[36:39], v[74:75], off offset:768
	v_add_co_u32_e32 v42, vcc, 0x1000, v74
	v_lshl_add_u64 v[40:41], v[74:75], 0, s[22:23]
	s_nop 0
	v_addc_co_u32_e32 v43, vcc, 0, v75, vcc
	global_load_dwordx4 v[44:47], v[42:43], off offset:768
	s_nop 0
	global_load_dwordx4 v[40:43], v[40:41], off offset:16
	s_and_b64 vcc, exec, s[6:7]
	s_waitcnt lgkmcnt(0)
	s_barrier
	s_cbranch_vccnz .LBB0_169
	ds_read_b128 v[64:67], v214
	ds_read_b128 v[72:75], v78 offset:36864
	s_waitcnt lgkmcnt(0)
	v_mfma_f32_16x16x32_bf16 v[64:67], v[64:67], v[72:75], 0
	ds_read_b128 v[72:75], v214 offset:64
	ds_read_b128 v[86:89], v78 offset:36928
	s_waitcnt lgkmcnt(0)
	v_mfma_f32_16x16x32_bf16 v[64:67], v[72:75], v[86:89], v[64:67]
	ds_read_b128 v[72:75], v214 offset:128
	ds_read_b128 v[86:89], v78 offset:36992
	s_waitcnt lgkmcnt(0)
	v_mfma_f32_16x16x32_bf16 v[64:67], v[72:75], v[86:89], v[64:67]
	ds_read_b128 v[72:75], v214 offset:192
	ds_read_b128 v[86:89], v78 offset:37056
	s_waitcnt lgkmcnt(0)
	v_mfma_f32_16x16x32_bf16 v[64:67], v[72:75], v[86:89], v[64:67]
	ds_read_b128 v[72:75], v214 offset:256
	ds_read_b128 v[86:89], v78 offset:37120
	s_waitcnt lgkmcnt(0)
	v_mfma_f32_16x16x32_bf16 v[64:67], v[72:75], v[86:89], v[64:67]
	ds_read_b128 v[72:75], v214 offset:320
	ds_read_b128 v[86:89], v78 offset:37184
	s_waitcnt lgkmcnt(0)
	v_mfma_f32_16x16x32_bf16 v[64:67], v[72:75], v[86:89], v[64:67]
	ds_read_b128 v[72:75], v214 offset:384
	ds_read_b128 v[86:89], v78 offset:37248
	s_waitcnt lgkmcnt(0)
	v_mfma_f32_16x16x32_bf16 v[64:67], v[72:75], v[86:89], v[64:67]
	ds_read_b128 v[72:75], v214 offset:448
	ds_read_b128 v[86:89], v78 offset:37312
	s_waitcnt lgkmcnt(0)
	v_mfma_f32_16x16x32_bf16 v[64:67], v[72:75], v[86:89], v[64:67]
	s_and_saveexec_b64 s[22:23], s[4:5]
	s_cbranch_execz .LBB0_168
	s_nop 5
	v_pk_mul_f32 v[64:65], v[68:69], v[64:65] op_sel_hi:[0,1]
	v_pk_mul_f32 v[66:67], v[68:69], v[66:67] op_sel_hi:[0,1]
	v_cvt_pk_bf16_f32 v64, v64, v65
	v_cvt_pk_bf16_f32 v65, v66, v67
	v_lshl_add_u64 v[66:67], s[20:21], 0, v[162:163]
	v_lshl_add_u64 v[66:67], v[66:67], 0, s[0:1]
	v_lshl_add_u64 v[66:67], s[16:17], 1, v[66:67]
	v_lshlrev_b32_e32 v152, 1, v98
	v_lshl_add_u64 v[66:67], v[66:67], 0, v[152:153]
	flat_store_dwordx2 v[66:67], v[64:65] offset:128

.LBB0_169:
	s_waitcnt vmcnt(8)
	v_cvt_pk_bf16_f32 v28, v28, v29
	v_cvt_pk_bf16_f32 v16, v16, v17
	v_cvt_pk_bf16_f32 v17, v18, v19
	v_cvt_pk_bf16_f32 v18, v24, v25
	v_cvt_pk_bf16_f32 v20, v20, v21
	v_cvt_pk_bf16_f32 v21, v22, v23
	v_and_b32_e32 v22, 0xffff, v28
	v_lshrrev_b32_e32 v23, 16, v28
	v_cvt_pk_bf16_f32 v29, v30, v31
	v_lshl_or_b32 v22, v18, 16, v22
	v_and_or_b32 v18, v18, s59, v23
	s_waitcnt lgkmcnt(0)
	s_barrier
	v_cvt_pk_bf16_f32 v19, v26, v27
	ds_write2_b32 v69, v22, v18 offset1:132
	v_and_b32_e32 v18, 0xffff, v29
	v_lshrrev_b32_e32 v22, 16, v29
	v_lshl_or_b32 v18, v19, 16, v18
	v_and_or_b32 v19, v19, s59, v22
	ds_write2_b32 v70, v18, v19 offset0:8 offset1:140
	v_and_b32_e32 v18, 0xffff, v16
	v_lshrrev_b32_e32 v16, 16, v16
	v_lshl_or_b32 v18, v20, 16, v18
	v_and_or_b32 v16, v20, s59, v16
	v_cvt_pk_bf16_f32 v4, v4, v5
	ds_write2_b32 v81, v18, v16 offset0:16 offset1:148
	v_and_b32_e32 v16, 0xffff, v17
	v_lshrrev_b32_e32 v17, 16, v17
	v_cvt_pk_bf16_f32 v0, v0, v1
	v_cvt_pk_bf16_f32 v1, v2, v3
	v_cvt_pk_bf16_f32 v2, v8, v9
	v_and_b32_e32 v8, 0xffff, v4
	v_lshrrev_b32_e32 v4, 16, v4
	v_lshl_or_b32 v16, v21, 16, v16
	v_and_or_b32 v17, v21, s59, v17
	v_cvt_pk_bf16_f32 v5, v6, v7
	v_lshl_or_b32 v8, v2, 16, v8
	v_and_or_b32 v2, v2, s59, v4
	ds_write2_b32 v82, v16, v17 offset0:24 offset1:156
	v_cvt_pk_bf16_f32 v3, v10, v11
	ds_write2_b32 v71, v8, v2 offset1:132
	v_and_b32_e32 v2, 0xffff, v5
	v_lshrrev_b32_e32 v4, 16, v5
	v_lshl_or_b32 v2, v3, 16, v2
	v_and_or_b32 v3, v3, s59, v4
	v_cvt_pk_bf16_f32 v6, v12, v13
	ds_write2_b32 v80, v2, v3 offset0:8 offset1:140
	v_and_b32_e32 v2, 0xffff, v0
	v_lshrrev_b32_e32 v0, 16, v0
	v_lshl_or_b32 v2, v6, 16, v2
	v_and_or_b32 v0, v6, s59, v0
	v_cvt_pk_bf16_f32 v7, v14, v15
	ds_write2_b32 v83, v2, v0 offset0:16 offset1:148
	v_and_b32_e32 v0, 0xffff, v1
	v_lshrrev_b32_e32 v1, 16, v1
	v_lshl_or_b32 v0, v7, 16, v0
	v_and_or_b32 v1, v7, s59, v1
	s_and_b64 vcc, exec, s[6:7]
	ds_write2_b32 v84, v0, v1 offset0:24 offset1:156
	s_waitcnt lgkmcnt(0)
	s_barrier
	s_cbranch_vccnz .LBB0_173
	ds_read_b128 v[0:3], v214
	ds_read_b128 v[4:7], v78 offset:36864
	s_waitcnt lgkmcnt(0)
	v_mfma_f32_16x16x32_bf16 v[0:3], v[0:3], v[4:7], 0
	ds_read_b128 v[4:7], v214 offset:64
	ds_read_b128 v[8:11], v78 offset:36928
	s_waitcnt lgkmcnt(0)
	v_mfma_f32_16x16x32_bf16 v[0:3], v[4:7], v[8:11], v[0:3]
	ds_read_b128 v[4:7], v214 offset:128
	ds_read_b128 v[8:11], v78 offset:36992
	s_waitcnt lgkmcnt(0)
	v_mfma_f32_16x16x32_bf16 v[0:3], v[4:7], v[8:11], v[0:3]
	ds_read_b128 v[4:7], v214 offset:192
	ds_read_b128 v[8:11], v78 offset:37056
	s_waitcnt lgkmcnt(0)
	v_mfma_f32_16x16x32_bf16 v[0:3], v[4:7], v[8:11], v[0:3]
	ds_read_b128 v[4:7], v214 offset:256
	ds_read_b128 v[8:11], v78 offset:37120
	s_waitcnt lgkmcnt(0)
	v_mfma_f32_16x16x32_bf16 v[0:3], v[4:7], v[8:11], v[0:3]
	ds_read_b128 v[4:7], v214 offset:320
	ds_read_b128 v[8:11], v78 offset:37184
	s_waitcnt lgkmcnt(0)
	v_mfma_f32_16x16x32_bf16 v[0:3], v[4:7], v[8:11], v[0:3]
	ds_read_b128 v[4:7], v214 offset:384
	ds_read_b128 v[8:11], v78 offset:37248
	s_waitcnt lgkmcnt(0)
	v_mfma_f32_16x16x32_bf16 v[0:3], v[4:7], v[8:11], v[0:3]
	ds_read_b128 v[4:7], v214 offset:448
	ds_read_b128 v[8:11], v78 offset:37312
	s_waitcnt lgkmcnt(0)
	v_mfma_f32_16x16x32_bf16 v[0:3], v[4:7], v[8:11], v[0:3]
	s_and_saveexec_b64 s[22:23], s[4:5]
	s_cbranch_execz .LBB0_172
	s_nop 5
	v_pk_mul_f32 v[0:1], v[68:69], v[0:1] op_sel_hi:[0,1]
	v_pk_mul_f32 v[2:3], v[68:69], v[2:3] op_sel_hi:[0,1]
	v_cvt_pk_bf16_f32 v0, v0, v1
	v_cvt_pk_bf16_f32 v1, v2, v3
	v_lshl_add_u64 v[2:3], s[20:21], 0, v[162:163]
	v_lshl_add_u64 v[2:3], v[2:3], 0, s[0:1]
	v_lshl_add_u64 v[2:3], s[16:17], 1, v[2:3]
	v_lshlrev_b32_e32 v152, 1, v98
	v_lshl_add_u64 v[2:3], v[2:3], 0, v[152:153]
	flat_store_dwordx2 v[2:3], v[0:1] offset:256

.LBB0_173:
	s_waitcnt vmcnt(0)
	s_nop 4
	v_cvt_pk_bf16_f32 v0, v60, v61
	v_cvt_pk_bf16_f32 v4, v56, v57
	v_and_b32_e32 v8, 0xffff, v0
	v_lshrrev_b32_e32 v0, 16, v0
	v_cvt_pk_bf16_f32 v1, v62, v63
	v_lshl_or_b32 v8, v4, 16, v8
	v_and_or_b32 v0, v4, s59, v0
	s_waitcnt lgkmcnt(0)
	s_barrier
	v_cvt_pk_bf16_f32 v5, v58, v59
	ds_write2_b32 v69, v8, v0 offset1:132
	v_and_b32_e32 v0, 0xffff, v1
	v_lshrrev_b32_e32 v1, 16, v1
	v_cvt_pk_bf16_f32 v2, v48, v49
	v_lshl_or_b32 v0, v5, 16, v0
	v_and_or_b32 v1, v5, s59, v1
	v_cvt_pk_bf16_f32 v6, v52, v53
	ds_write2_b32 v70, v0, v1 offset0:8 offset1:140
	v_and_b32_e32 v0, 0xffff, v2
	v_lshrrev_b32_e32 v1, 16, v2
	v_cvt_pk_bf16_f32 v3, v50, v51
	v_lshl_or_b32 v0, v6, 16, v0
	v_and_or_b32 v1, v6, s59, v1
	v_cvt_pk_bf16_f32 v7, v54, v55
	ds_write2_b32 v81, v0, v1 offset0:16 offset1:148
	v_and_b32_e32 v0, 0xffff, v3
	v_lshrrev_b32_e32 v1, 16, v3
	v_lshl_or_b32 v0, v7, 16, v0
	v_and_or_b32 v1, v7, s59, v1
	ds_write2_b32 v82, v0, v1 offset0:24 offset1:156
	v_cvt_pk_bf16_f32 v0, v36, v37
	v_cvt_pk_bf16_f32 v4, v44, v45
	v_and_b32_e32 v8, 0xffff, v0
	v_lshrrev_b32_e32 v0, 16, v0
	v_cvt_pk_bf16_f32 v1, v38, v39
	v_lshl_or_b32 v8, v4, 16, v8
	v_and_or_b32 v0, v4, s59, v0
	v_cvt_pk_bf16_f32 v5, v46, v47
	ds_write2_b32 v71, v8, v0 offset1:132
	v_and_b32_e32 v0, 0xffff, v1
	v_lshrrev_b32_e32 v1, 16, v1
	v_cvt_pk_bf16_f32 v2, v32, v33
	v_lshl_or_b32 v0, v5, 16, v0
	v_and_or_b32 v1, v5, s59, v1
	v_cvt_pk_bf16_f32 v6, v40, v41
	ds_write2_b32 v80, v0, v1 offset0:8 offset1:140
	v_and_b32_e32 v0, 0xffff, v2
	v_lshrrev_b32_e32 v1, 16, v2
	v_cvt_pk_bf16_f32 v3, v34, v35
	v_lshl_or_b32 v0, v6, 16, v0
	v_and_or_b32 v1, v6, s59, v1
	v_cvt_pk_bf16_f32 v7, v42, v43
	ds_write2_b32 v83, v0, v1 offset0:16 offset1:148
	v_and_b32_e32 v0, 0xffff, v3
	v_lshrrev_b32_e32 v1, 16, v3
	v_lshl_or_b32 v0, v7, 16, v0
	v_and_or_b32 v1, v7, s59, v1
	s_and_b64 vcc, exec, s[6:7]
	ds_write2_b32 v84, v0, v1 offset0:24 offset1:156
	s_waitcnt lgkmcnt(0)
	s_barrier
	s_cbranch_vccnz .LBB0_177
	ds_read_b128 v[0:3], v214
	ds_read_b128 v[4:7], v78 offset:36864
	s_waitcnt lgkmcnt(0)
	v_mfma_f32_16x16x32_bf16 v[0:3], v[0:3], v[4:7], 0
	ds_read_b128 v[4:7], v214 offset:64
	ds_read_b128 v[8:11], v78 offset:36928
	s_waitcnt lgkmcnt(0)
	v_mfma_f32_16x16x32_bf16 v[0:3], v[4:7], v[8:11], v[0:3]
	ds_read_b128 v[4:7], v214 offset:128
	ds_read_b128 v[8:11], v78 offset:36992
	s_waitcnt lgkmcnt(0)
	v_mfma_f32_16x16x32_bf16 v[0:3], v[4:7], v[8:11], v[0:3]
	ds_read_b128 v[4:7], v214 offset:192
	ds_read_b128 v[8:11], v78 offset:37056
	s_waitcnt lgkmcnt(0)
	v_mfma_f32_16x16x32_bf16 v[0:3], v[4:7], v[8:11], v[0:3]
	ds_read_b128 v[4:7], v214 offset:256
	ds_read_b128 v[8:11], v78 offset:37120
	s_waitcnt lgkmcnt(0)
	v_mfma_f32_16x16x32_bf16 v[0:3], v[4:7], v[8:11], v[0:3]
	ds_read_b128 v[4:7], v214 offset:320
	ds_read_b128 v[8:11], v78 offset:37184
	s_waitcnt lgkmcnt(0)
	v_mfma_f32_16x16x32_bf16 v[0:3], v[4:7], v[8:11], v[0:3]
	ds_read_b128 v[4:7], v214 offset:384
	ds_read_b128 v[8:11], v78 offset:37248
	s_waitcnt lgkmcnt(0)
	v_mfma_f32_16x16x32_bf16 v[0:3], v[4:7], v[8:11], v[0:3]
	ds_read_b128 v[4:7], v214 offset:448
	ds_read_b128 v[8:11], v78 offset:37312
	s_waitcnt lgkmcnt(0)
	v_mfma_f32_16x16x32_bf16 v[0:3], v[4:7], v[8:11], v[0:3]
	s_and_saveexec_b64 s[6:7], s[4:5]
	s_cbranch_execz .LBB0_176
	s_nop 5
	v_pk_mul_f32 v[0:1], v[68:69], v[0:1] op_sel_hi:[0,1]
	v_pk_mul_f32 v[2:3], v[68:69], v[2:3] op_sel_hi:[0,1]
	v_cvt_pk_bf16_f32 v0, v0, v1
	v_cvt_pk_bf16_f32 v1, v2, v3
	v_lshl_add_u64 v[2:3], s[20:21], 0, v[162:163]
	v_lshl_add_u64 v[2:3], v[2:3], 0, s[0:1]
	v_lshl_add_u64 v[2:3], s[16:17], 1, v[2:3]
	v_lshlrev_b32_e32 v152, 1, v98
	v_lshl_add_u64 v[2:3], v[2:3], 0, v[152:153]
	flat_store_dwordx2 v[2:3], v[0:1] offset:384

.LBB0_183:
	v_add_u32_e32 v44, s0, v181
	v_add_u32_e32 v36, 0x11000, v44
	v_add_u32_e32 v45, s0, v177
	v_add_u32_e32 v46, s0, v178
	v_add_u32_e32 v47, s0, v179
	v_add_u32_e32 v48, s0, v180
	ds_read_b128 v[36:39], v36
	ds_read_b128 v[40:43], v45
	ds_read_b128 v[224:227], v46
	ds_read_b128 v[228:231], v46 offset:8448
	ds_read_b128 v[232:235], v47
	ds_read_b128 v[236:239], v46 offset:25344
	ds_read_b128 v[240:243], v46 offset:33792
	ds_read_b128 v[244:247], v46 offset:42240
	ds_read_b128 v[248:251], v48
	s_addk_i32 s0, 0x80
	s_cmpk_eq_i32 s0, 0x200
	s_waitcnt lgkmcnt(7)
	v_mfma_f32_16x16x32_bf16 v[24:27], v[40:43], v[36:39], v[24:27]
	s_waitcnt lgkmcnt(6)
	v_mfma_f32_16x16x32_bf16 v[20:23], v[224:227], v[36:39], v[20:23]
	s_waitcnt lgkmcnt(5)
	v_mfma_f32_16x16x32_bf16 v[12:15], v[228:231], v[36:39], v[12:15]
	s_waitcnt lgkmcnt(4)
	v_mfma_f32_16x16x32_bf16 v[8:11], v[232:235], v[36:39], v[8:11]
	s_waitcnt lgkmcnt(3)
	v_mfma_f32_16x16x32_bf16 v[4:7], v[236:239], v[36:39], v[4:7]
	s_waitcnt lgkmcnt(2)
	v_mfma_f32_16x16x32_bf16 v[0:3], v[240:243], v[36:39], v[0:3]
	s_waitcnt lgkmcnt(1)
	v_mfma_f32_16x16x32_bf16 v[16:19], v[244:247], v[36:39], v[16:19]
	s_waitcnt lgkmcnt(0)
	v_mfma_f32_16x16x32_bf16 v[28:31], v[248:251], v[36:39], v[28:31]
	v_add_u32_e32 v36, 0x11040, v44
	ds_read_b128 v[36:39], v36
	ds_read_b128 v[40:43], v45 offset:64
	ds_read_b128 v[224:227], v46 offset:64
	ds_read_b128 v[228:231], v46 offset:8512
	ds_read_b128 v[232:235], v47 offset:64
	ds_read_b128 v[236:239], v46 offset:25408
	ds_read_b128 v[240:243], v46 offset:33856
	ds_read_b128 v[244:247], v46 offset:42304
	ds_read_b128 v[248:251], v48 offset:64
	s_waitcnt lgkmcnt(7)
	v_mfma_f32_16x16x32_bf16 v[24:27], v[40:43], v[36:39], v[24:27]
	s_waitcnt lgkmcnt(6)
	v_mfma_f32_16x16x32_bf16 v[20:23], v[224:227], v[36:39], v[20:23]
	s_waitcnt lgkmcnt(5)
	v_mfma_f32_16x16x32_bf16 v[12:15], v[228:231], v[36:39], v[12:15]
	s_waitcnt lgkmcnt(4)
	v_mfma_f32_16x16x32_bf16 v[8:11], v[232:235], v[36:39], v[8:11]
	s_waitcnt lgkmcnt(3)
	v_mfma_f32_16x16x32_bf16 v[4:7], v[236:239], v[36:39], v[4:7]
	s_waitcnt lgkmcnt(2)
	v_mfma_f32_16x16x32_bf16 v[0:3], v[240:243], v[36:39], v[0:3]
	s_waitcnt lgkmcnt(1)
	v_mfma_f32_16x16x32_bf16 v[16:19], v[244:247], v[36:39], v[16:19]
	s_waitcnt lgkmcnt(0)
	v_mfma_f32_16x16x32_bf16 v[28:31], v[248:251], v[36:39], v[28:31]
	s_cbranch_scc0 .LBB0_183
	s_nop 3
	v_pk_mul_f32 v[0:1], v[32:33], v[0:1]
	v_pk_mul_f32 v[2:3], v[32:33], v[2:3]
	v_lshl_add_u64 v[36:37], s[22:23], 1, v[34:35]
	v_cvt_pk_bf16_f32 v0, v0, v1
	v_cvt_pk_bf16_f32 v1, v2, v3
	flat_store_dwordx2 v[36:37], v[0:1] offset:160
	v_pk_mul_f32 v[0:1], v[32:33], v[16:17]
	v_pk_mul_f32 v[2:3], v[32:33], v[18:19]
	v_cvt_pk_bf16_f32 v0, v0, v1
	v_cvt_pk_bf16_f32 v1, v2, v3
	v_pk_mul_f32 v[24:25], v[32:33], v[24:25]
	v_pk_mul_f32 v[26:27], v[32:33], v[26:27]
	v_pk_mul_f32 v[20:21], v[32:33], v[20:21]
	v_pk_mul_f32 v[22:23], v[32:33], v[22:23]
	v_pk_mul_f32 v[12:13], v[32:33], v[12:13]
	v_pk_mul_f32 v[14:15], v[32:33], v[14:15]
	v_pk_mul_f32 v[8:9], v[32:33], v[8:9]
	v_pk_mul_f32 v[10:11], v[32:33], v[10:11]
	v_pk_mul_f32 v[4:5], v[32:33], v[4:5]
	v_pk_mul_f32 v[6:7], v[32:33], v[6:7]
	flat_store_dwordx2 v[36:37], v[0:1] offset:192
	v_pk_mul_f32 v[0:1], v[32:33], v[28:29]
	v_pk_mul_f32 v[2:3], v[32:33], v[30:31]
	v_cvt_pk_bf16_f32 v24, v24, v25
	v_cvt_pk_bf16_f32 v25, v26, v27
	v_cvt_pk_bf16_f32 v20, v20, v21
	v_cvt_pk_bf16_f32 v21, v22, v23
	v_cvt_pk_bf16_f32 v12, v12, v13
	v_cvt_pk_bf16_f32 v13, v14, v15
	v_cvt_pk_bf16_f32 v8, v8, v9
	v_cvt_pk_bf16_f32 v9, v10, v11
	v_cvt_pk_bf16_f32 v4, v4, v5
	v_cvt_pk_bf16_f32 v5, v6, v7
	v_cvt_pk_bf16_f32 v0, v0, v1
	v_cvt_pk_bf16_f32 v1, v2, v3
	s_mov_b64 s[22:23], 0x80
	s_mov_b64 s[24:25], 0
	s_and_b64 vcc, exec, s[20:21]
	flat_store_dwordx2 v[36:37], v[24:25]
	flat_store_dwordx2 v[36:37], v[20:21] offset:32
	flat_store_dwordx2 v[36:37], v[12:13] offset:64
	flat_store_dwordx2 v[36:37], v[8:9] offset:96
	flat_store_dwordx2 v[36:37], v[4:5] offset:128
	flat_store_dwordx2 v[36:37], v[0:1] offset:224
	s_waitcnt lgkmcnt(0)
	s_barrier
	s_cbranch_vccz .LBB0_182
	s_branch .LBB0_150

.LBB0_285:
	s_or_b64 exec, exec, s[10:11]
	v_mov_b32_e32 v0, s86
	s_waitcnt lgkmcnt(0)
	s_barrier
	ds_read_b32 v0, v0
	s_movk_i32 s0, 0x4ff
	s_mov_b64 s[10:11], -1
	s_waitcnt lgkmcnt(0)
	v_cmp_lt_i32_e32 vcc, s0, v0
	v_readfirstlane_b32 s68, v0
	s_cbranch_vccnz .LBB0_282
	s_add_i32 s0, s68, 0xffffff80
	s_cmpk_lt_u32 s0, 0x400
	s_cbranch_scc0 .Lp3_map_done
	s_lshr_b32 vcc_lo, s0, 1
	s_bitcmp1_b32 s0, 0
	s_cselect_b32 s0, 0, 0x200
	s_add_i32 s68, vcc_lo, s0
	s_addk_i32 s68, 0x80
.Lp3_map_done:
	s_cmpk_gt_i32 s68, 0x7f
	s_cbranch_scc0 .LBB0_306
	s_cmpk_gt_u32 s68, 0x27f
	s_cbranch_scc0 .LBB0_302
	s_cmpk_gt_u32 s68, 0x47f
	s_cbranch_scc0 .LBB0_290
	s_mov_b64 s[52:53], s[94:95]
	s_add_u32 s4, s52, 0xc700000
	s_addc_u32 s5, s53, 0
	s_lshl_b32 s0, s68, 3
	s_addk_i32 s0, 0x1c00
	s_mul_i32 s10, s0, 0x2800
	s_mul_hi_u32 s11, s0, 0x2800
	s_add_u32 s10, s4, s10
	v_lshl_add_u64 v[2:3], s[4:5], 0, v[128:129]
	v_mov_b32_e32 v1, 0x2800
	s_addc_u32 s11, s5, s11
	v_mad_u64_u32 v[16:17], s[4:5], s0, v1, v[2:3]
	v_lshl_add_u64 v[22:23], s[10:11], 0, v[128:129]
	s_movk_i32 s10, 0x3000
	s_movk_i32 s4, 0x2000
	flat_load_dword v15, v[22:23] offset:2048
	v_add_co_u32_e32 v0, vcc, s10, v22
	v_add_co_u32_e64 v2, s[10:11], s4, v16
	s_nop 0
	v_addc_co_u32_e32 v1, vcc, 0, v23, vcc
	v_addc_co_u32_e64 v3, s[10:11], 0, v17, s[10:11]
	flat_load_dword v21, v[2:3] offset:2048
	global_load_dwordx4 v[4:7], v[66:67], off
	global_load_dwordx2 v[26:27], v[64:65], off offset:512
	flat_load_dword v38, v[0:1]
	s_nop 0
	global_load_dwordx4 v[0:3], v[66:67], off offset:16
	global_load_dwordx3 v[12:14], v[64:65], off offset:1024
	global_load_dword v20, v[64:65], off
	global_load_dwordx4 v[8:11], v[64:65], off offset:1536
	v_lshl_add_u64 v[18:19], s[52:53], 0, v[128:129]
	s_mov_b64 s[4:5], 0x17100000
	v_lshl_add_u64 v[18:19], v[18:19], 0, s[4:5]
	s_movk_i32 s4, 0x7000
	v_add_co_u32_e32 v24, vcc, s4, v16
	s_mov_b32 s4, 0x11000
	s_nop 0
	v_addc_co_u32_e32 v25, vcc, 0, v17, vcc
	v_add_co_u32_e32 v28, vcc, s4, v16
	s_lshl_b64 s[10:11], s[0:1], 12
	s_nop 0
	v_addc_co_u32_e32 v29, vcc, 0, v17, vcc
	s_or_b32 s4, s10, 0x1000
	s_mov_b32 s5, s11
	flat_load_dword v39, v[24:25] offset:2048
	flat_load_dword v44, v[28:29] offset:2048
	flat_load_dword v41, v[16:17]
	v_lshl_add_u64 v[28:29], v[18:19], 0, s[4:5]
	s_movk_i32 s4, 0x5000
	v_add_co_u32_e32 v24, vcc, s4, v22
	s_mov_b32 s0, 0x8000
	s_nop 0
	v_addc_co_u32_e32 v25, vcc, 0, v23, vcc
	v_add_co_u32_e32 v30, vcc, s0, v22
	s_mov_b32 s5, 0xa000
	s_nop 0
	v_addc_co_u32_e32 v31, vcc, 0, v23, vcc
	v_add_co_u32_e32 v32, vcc, s5, v22
	s_mov_b32 s0, 0xd000
	s_nop 0
	v_addc_co_u32_e32 v33, vcc, 0, v23, vcc
	v_add_co_u32_e32 v34, vcc, s0, v22
	s_mov_b32 s52, 0xf000
	s_nop 0
	v_addc_co_u32_e32 v35, vcc, 0, v23, vcc
	v_add_co_u32_e32 v36, vcc, s52, v22
	s_mov_b32 s0, 0x12000
	s_nop 0
	v_addc_co_u32_e32 v37, vcc, 0, v23, vcc
	v_add_co_u32_e32 v22, vcc, s0, v22
	s_mov_b32 s0, 0xc000
	s_nop 0
	v_addc_co_u32_e32 v23, vcc, 0, v23, vcc
	flat_load_dword v45, v[24:25] offset:2048
	flat_load_dword v46, v[30:31]
	flat_load_dword v47, v[32:33] offset:2048
	flat_load_dword v48, v[34:35]
	flat_load_dword v49, v[36:37] offset:2048
	flat_load_dword v50, v[22:23]
	s_or_b32 s12, s10, 0x3000
	s_mov_b32 s13, s11
	v_lshl_add_u64 v[34:35], v[18:19], 0, s[12:13]
	s_waitcnt vmcnt(0) lgkmcnt(0)
	v_lshlrev_b32_e32 v24, 16, v15
	v_and_b32_e32 v25, 0xffff0000, v15
	v_mov_b32_e32 v36, v7
	v_pk_fma_f32 v[32:33], v[26:27], v[24:25], v[4:5] op_sel:[0,0,1] op_sel_hi:[0,1,1]
	v_lshlrev_b32_e32 v22, 16, v38
	v_and_b32_e32 v23, 0xffff0000, v38
	v_pk_fma_f32 v[26:27], v[26:27], v[22:23], v[32:33] op_sel:[1,0,0]
	v_lshlrev_b32_e32 v30, 16, v21
	v_and_b32_e32 v31, 0xffff0000, v21
	v_pk_mul_f32 v[26:27], v[26:27], v[30:31]
	v_pk_fma_f32 v[4:5], v[20:21], v[24:25], v[4:5] op_sel_hi:[0,1,0]
	v_cvt_pk_bf16_f32 v15, v26, v27
	v_add_co_u32_e32 v26, vcc, s4, v16
	flat_store_dword v[28:29], v15
	s_nop 0
	v_addc_co_u32_e32 v27, vcc, 0, v17, vcc
	flat_load_dword v15, v[26:27]
	v_pk_fma_f32 v[6:7], v[12:13], v[24:25], v[6:7] op_sel_hi:[0,1,0]
	v_pk_fma_f32 v[20:21], v[8:9], v[24:25], v[36:37] op_sel_hi:[0,1,0]
	v_mov_b32_e32 v38, v11
	v_add_co_u32_e32 v26, vcc, s5, v16
	v_lshlrev_b32_e32 v42, 16, v39
	v_and_b32_e32 v43, 0xffff0000, v39
	v_lshlrev_b32_e32 v40, 16, v41
	v_and_b32_e32 v41, 0xffff0000, v41
	v_pk_mul_f32 v[4:5], v[4:5], v[40:41]
	v_addc_co_u32_e32 v27, vcc, 0, v17, vcc
	v_cvt_pk_bf16_f32 v39, v4, v5
	v_pk_fma_f32 v[4:5], v[12:13], v[22:23], v[6:7] op_sel:[1,0,0]
	v_pk_fma_f32 v[6:7], v[8:9], v[22:23], v[20:21] op_sel:[1,0,0]
	s_or_b32 s4, s10, 0x2000
	s_mov_b32 s5, s11
	v_add_co_u32_e32 v28, vcc, s0, v16
	v_lshl_add_u64 v[30:31], v[18:19], 0, s[10:11]
	v_lshl_add_u64 v[32:33], v[18:19], 0, s[4:5]
	v_addc_co_u32_e32 v29, vcc, 0, v17, vcc
	flat_store_dword v[30:31], v39
	flat_load_dword v28, v[28:29] offset:2048
	s_or_b32 s4, s10, 0x4000
	v_lshlrev_b32_e32 v36, 16, v45
	v_and_b32_e32 v37, 0xffff0000, v45
	v_lshlrev_b32_e32 v12, 16, v46
	v_and_b32_e32 v13, 0xffff0000, v46
	v_pk_fma_f32 v[6:7], v[10:11], v[36:37], v[6:7] op_sel_hi:[0,1,1]
	v_pk_fma_f32 v[6:7], v[38:39], v[12:13], v[6:7] op_sel_hi:[0,1,1]
	v_pk_mul_f32 v[6:7], v[6:7], v[42:43]
	v_add_co_u32_e32 v10, vcc, s52, v16
	v_cvt_pk_bf16_f32 v8, v6, v7
	flat_store_dword v[34:35], v8
	v_addc_co_u32_e32 v11, vcc, 0, v17, vcc
	v_lshlrev_b32_e32 v16, 16, v47
	v_and_b32_e32 v17, 0xffff0000, v47
	s_waitcnt vmcnt(0) lgkmcnt(0)
	v_pk_fma_f32 v[4:5], v[14:15], v[36:37], v[4:5] op_sel_hi:[0,1,1]
	v_lshlrev_b32_e32 v6, 16, v15
	v_and_b32_e32 v7, 0xffff0000, v15
	v_pk_mul_f32 v[4:5], v[4:5], v[6:7]
	v_lshl_add_u64 v[14:15], v[18:19], 0, s[4:5]
	v_cvt_pk_bf16_f32 v4, v4, v5
	flat_store_dword v[32:33], v4
	flat_load_dword v9, v[26:27]
	s_nop 0
	global_load_dwordx4 v[4:7], v[64:65], off offset:2048
	global_load_dword v8, v[64:65], off offset:2064
	flat_load_dword v27, v[10:11]
	s_or_b32 s4, s10, 0x5000
	s_waitcnt vmcnt(0)
	v_pk_fma_f32 v[20:21], v[4:5], v[24:25], v[0:1] op_sel_hi:[0,1,0]
	v_pk_fma_f32 v[4:5], v[4:5], v[22:23], v[20:21] op_sel:[1,0,0]
	v_mov_b32_e32 v26, v7
	v_pk_fma_f32 v[4:5], v[6:7], v[36:37], v[4:5] op_sel_hi:[0,1,1]
	s_waitcnt lgkmcnt(0)
	v_pk_fma_f32 v[4:5], v[26:27], v[12:13], v[4:5] op_sel_hi:[0,1,1]
	v_lshlrev_b32_e32 v10, 16, v9
	v_and_b32_e32 v11, 0xffff0000, v9
	v_pk_fma_f32 v[4:5], v[8:9], v[16:17], v[4:5] op_sel_hi:[0,1,1]
	v_pk_mul_f32 v[4:5], v[4:5], v[10:11]
	v_lshlrev_b32_e32 v20, 16, v28
	v_cvt_pk_bf16_f32 v4, v4, v5
	flat_store_dword v[14:15], v4
	global_load_dwordx4 v[4:7], v[64:65], off offset:2560
	s_nop 0
	global_load_dwordx2 v[8:9], v[64:65], off offset:2576
	v_lshlrev_b32_e32 v14, 16, v48
	v_and_b32_e32 v15, 0xffff0000, v48
	v_and_b32_e32 v21, 0xffff0000, v28
	v_lshl_add_u64 v[10:11], v[18:19], 0, s[4:5]
	s_or_b32 s4, s10, 0x6000
	s_or_b32 s10, s10, 0x7000
	s_waitcnt vmcnt(0)
	v_pk_fma_f32 v[0:1], v[4:5], v[24:25], v[0:1] op_sel:[0,0,1] op_sel_hi:[0,1,1]
	v_pk_fma_f32 v[0:1], v[4:5], v[22:23], v[0:1] op_sel:[1,0,0]
	v_mov_b32_e32 v26, v7
	v_pk_fma_f32 v[0:1], v[6:7], v[36:37], v[0:1] op_sel_hi:[0,1,1]
	v_pk_fma_f32 v[0:1], v[26:27], v[12:13], v[0:1] op_sel_hi:[0,1,1]
	v_pk_fma_f32 v[0:1], v[8:9], v[16:17], v[0:1] op_sel_hi:[0,1,1]
	v_pk_fma_f32 v[0:1], v[8:9], v[14:15], v[0:1] op_sel:[1,0,0]
	v_lshlrev_b32_e32 v26, 16, v27
	v_pk_mul_f32 v[0:1], v[0:1], v[20:21]
	v_lshlrev_b32_e32 v20, 16, v49
	v_cvt_pk_bf16_f32 v0, v0, v1
	flat_store_dword v[10:11], v0
	global_load_dwordx4 v[4:7], v[64:65], off offset:3072
	s_nop 0
	global_load_dwordx3 v[8:10], v[64:65], off offset:3088
	v_and_b32_e32 v21, 0xffff0000, v49
	v_and_b32_e32 v27, 0xffff0000, v27
	v_lshl_add_u64 v[0:1], v[18:19], 0, s[4:5]
	s_waitcnt vmcnt(0)
	v_pk_fma_f32 v[28:29], v[4:5], v[24:25], v[2:3] op_sel_hi:[0,1,0]
	v_pk_fma_f32 v[4:5], v[4:5], v[22:23], v[28:29] op_sel:[1,0,0]
	v_mov_b32_e32 v2, v7
	v_pk_fma_f32 v[4:5], v[6:7], v[36:37], v[4:5] op_sel_hi:[0,1,1]
	v_pk_fma_f32 v[4:5], v[2:3], v[12:13], v[4:5] op_sel_hi:[0,1,1]
	v_pk_fma_f32 v[4:5], v[8:9], v[16:17], v[4:5] op_sel_hi:[0,1,1]
	v_pk_fma_f32 v[4:5], v[8:9], v[14:15], v[4:5] op_sel:[1,0,0]
	s_nop 0
	v_pk_fma_f32 v[4:5], v[10:11], v[20:21], v[4:5] op_sel_hi:[0,1,1]
	v_pk_mul_f32 v[4:5], v[4:5], v[26:27]
	v_and_b32_e32 v27, 0xffff0000, v50
	v_cvt_pk_bf16_f32 v2, v4, v5
	flat_store_dword v[0:1], v2
	global_load_dwordx4 v[4:7], v[64:65], off offset:3584
	global_load_dwordx4 v[8:11], v[64:65], off offset:3600
	v_mov_b32_e32 v2, v3
	v_lshlrev_b32_e32 v26, 16, v50
	v_lshl_add_u64 v[0:1], v[18:19], 0, s[10:11]
	v_lshlrev_b32_e32 v18, 16, v44
	v_and_b32_e32 v19, 0xffff0000, v44
	s_mov_b64 s[10:11], 0
	s_waitcnt vmcnt(0)
	v_pk_fma_f32 v[2:3], v[4:5], v[24:25], v[2:3] op_sel_hi:[0,1,0]
	v_pk_fma_f32 v[2:3], v[4:5], v[22:23], v[2:3] op_sel:[1,0,0]
	v_mov_b32_e32 v24, v7
	v_pk_fma_f32 v[2:3], v[6:7], v[36:37], v[2:3] op_sel_hi:[0,1,1]
	v_pk_fma_f32 v[2:3], v[24:25], v[12:13], v[2:3] op_sel_hi:[0,1,1]
	v_pk_fma_f32 v[2:3], v[8:9], v[16:17], v[2:3] op_sel_hi:[0,1,1]
	v_pk_fma_f32 v[2:3], v[8:9], v[14:15], v[2:3] op_sel:[1,0,0]
	v_mov_b32_e32 v28, v11
	v_pk_fma_f32 v[2:3], v[10:11], v[20:21], v[2:3] op_sel_hi:[0,1,1]
	v_pk_fma_f32 v[2:3], v[28:29], v[26:27], v[2:3] op_sel_hi:[0,1,1]
	v_pk_mul_f32 v[2:3], v[2:3], v[18:19]
	s_nop 0
	v_cvt_pk_bf16_f32 v2, v2, v3
	flat_store_dword v[0:1], v2
